# grid barrier: non-leader release poll without the sleep between polls
# speedup vs baseline: 1.0012x; 1.0012x over previous
.LBB0_1509:
	global_load_dword v0, v153, s[12:13] sc1
	s_waitcnt vmcnt(0)
	v_cmp_ne_u32_e32 vcc, v0, v1
	s_or_b64 s[16:17], vcc, s[16:17]
	s_andn2_b64 exec, exec, s[16:17]
	s_cbranch_execnz .LBB0_1509
